# split variant A: GEMM workgroups convert ffn_w_gate L1 + ffn_w_up L1 + cd_w_out after their tiles (8-9 chunks per wave), converter workgroups 46-47 chunks per wave
# baseline (speedup 1.0000x reference)
; #define TR_JOB_GU(W_, WT_, off_, gain_) { constexpr int nnb_ = DFF / 32, nit_ = (DM / 64) * nnb_; \
;     if (r < nit_) { const int kb_ = r / nnb_, nb_ = r % nnb_, c0_ = 32 * nb_; \
;         return TrDesc{(W_) + (size_t)(64 * kb_) * DFF + c0_, (WT_) + (size_t)(256 * (c0_ / 128) + (c0_ % 128) + (off_)) * DM + 64 * kb_, (gain_) + 64 * kb_, DFF, DM}; } r -= nit_; }
; __device__ __forceinline__ TrDesc p0_item(const Params& p, int it) {
;     unsigned char* ws = p.ws;
;     bf16_t* WAB_IN = (bf16_t*)(ws + WS_WAB_IN); bf16_t* WAB_OUT = (bf16_t*)(ws + WS_WAB_OUT); bf16_t* WGU0 = (bf16_t*)(ws + WS_WGU0); bf16_t* WDN0 = (bf16_t*)(ws + WS_WDN0);
;     bf16_t* WCD_IN = (bf16_t*)(ws + WS_WCD_IN); bf16_t* WGU1 = (bf16_t*)(ws + WS_WGU1);
;     bf16_t* WRG = (bf16_t*)(ws + WS_WRG);
;     int r = it;
;     TR_JOB(p.ab_w_in, AB_IN, DM, 0, 6144, WAB_IN, 0, p.norm_mix)
;     TR_JOB(p.ab_w_in, AB_IN, DM, 6160, 6144, WAB_IN, 6144, p.norm_mix)
;     TR_JOB(p.ab_w_out, DM, DM, 0, DM, WAB_OUT, 0, (const float*)nullptr)
;     TR_JOB_GU(p.ffn_w_gate, WGU0, 0, p.norm_ffn)
;     TR_JOB_GU(p.ffn_w_up, WGU0, 128, p.norm_ffn)
;     TR_JOB(p.ffn_w_down, DM, DFF, 0, DM, WDN0, 0, (const float*)nullptr)
;     TR_JOB(p.cd_w_in, CD_IN, DM, 0, CD_IN, WCD_IN, 0, p.norm_mix + DM)
;     TR_JOB_GU(p.ffn_w_gate + (size_t)DM * DFF, WGU1, 0, p.norm_ffn + DM)
;     TR_JOB_GU(p.ffn_w_up + (size_t)DM * DFF, WGU1, 128, p.norm_ffn + DM)
;     TR_JOB(p.cd_w_out, DM, DM, 0, DM, (bf16_t*)(ws + WS_WCD_OUT), 0, (const float*)nullptr)
;     const int mat = r / 32, rr = r % 32, kb_ = rr / 8, nb_ = rr % 8;
;     const float* W = (mat < 8 ? p.rg_w_x : p.rg_w_a) + (size_t)(mat & 7) * 65536;
;     return TrDesc{W + (size_t)(64 * kb_) * 256 + 32 * nb_, WRG + (size_t)mat * 65536 + (size_t)(32 * nb_) * 256 + 64 * kb_, nullptr, 256, 256};
; }
.Lcv_job_abo:
	s_load_dwordx2 s[60:61], s[24:25], 0x58
	s_load_dwordx2 s[62:63], s[24:25], 0xb8
	s_mov_b32 s6, 0x4000
	s_mov_b32 s7, 0x2000
	s_mov_b32 s75, 0
	s_and_b32 s9, s18, 63
	s_lshr_b32 s10, s18, 6
	s_add_i32 s10, s10, 4
	s_and_b32 s10, s10, 7
	s_sub_i32 s74, 31, s10
	s_lshr_b32 s74, s74, 3
	s_add_i32 s74, s74, 1
	s_lshl_b32 s11, s9, 6
	s_mul_i32 s11, s11, s6
	s_lshl_b32 s21, s10, 9
	s_add_u32 s11, s11, s21
	s_mul_i32 s23, s10, 128
	s_mul_i32 s23, s23, s7
	s_lshl_b32 s26, s9, 7
	s_add_u32 s23, s23, s26
	s_mov_b32 s70, 0x1000
	s_mov_b32 s71, 0
	s_mov_b32 s72, 0x800000
	s_mov_b32 s73, 0
	s_waitcnt lgkmcnt(0)
	s_add_u32 s60, s60, s11
	s_addc_u32 s61, s61, 0
	s_add_u32 s62, s62, 0x6100000
	s_addc_u32 s63, s63, 0
	s_add_u32 s62, s62, s23
	s_addc_u32 s63, s63, 0
	s_lshl_b32 s26, s7, 5
	s_add_u32 s64, s62, s26
	s_addc_u32 s65, s63, 0
	s_add_u32 s66, s64, s26
	s_addc_u32 s67, s65, 0
	s_add_u32 s68, s66, s26
	s_addc_u32 s69, s67, 0
	s_mov_b32 s8, 0
	s_branch .Lcv_run
.Lcv_back_0:
.Lcv_job_g0:
	s_load_dwordx2 s[60:61], s[24:25], 0x18
	s_load_dwordx2 s[62:63], s[24:25], 0xb8
	s_load_dwordx2 s[4:5], s[24:25], 0x10
	s_mov_b32 s6, 0xac00
	s_mov_b32 s7, 0x2000
	s_mov_b32 s75, 1
	s_and_b32 s9, s18, 63
	s_lshr_b32 s10, s18, 6
	s_add_i32 s10, s10, 3
	s_and_b32 s10, s10, 7
	s_sub_i32 s74, 85, s10
	s_lshr_b32 s74, s74, 3
	s_add_i32 s74, s74, 1
	s_lshl_b32 s11, s9, 6
	s_mul_i32 s11, s11, s6
	s_lshl_b32 s21, s10, 9
	s_add_u32 s11, s11, s21
	s_mul_i32 s23, s10, 256
	s_mul_i32 s23, s23, s7
	s_lshl_b32 s26, s9, 7
	s_add_u32 s23, s23, s26
	s_mov_b32 s70, 0x1000
	s_mov_b32 s71, 0
	s_mov_b32 s72, 0x1000000
	s_mov_b32 s73, 0
	s_waitcnt lgkmcnt(0)
	s_add_u32 s60, s60, s11
	s_addc_u32 s61, s61, 0
	s_add_u32 s62, s62, 0x8100000
	s_addc_u32 s63, s63, 0
	s_add_u32 s62, s62, s23
	s_addc_u32 s63, s63, 0
	s_lshl_b32 s26, s7, 5
	s_add_u32 s64, s62, s26
	s_addc_u32 s65, s63, 0
	s_add_u32 s66, s64, s26
	s_addc_u32 s67, s65, 0
	s_add_u32 s68, s66, s26
	s_addc_u32 s69, s67, 0
	s_lshl_b32 s26, s9, 8
	s_add_u32 s4, s4, s26
	s_addc_u32 s5, s5, 0
	s_mov_b32 s8, 1
	s_branch .Lcv_run

; #define TR_JOB_GU(W_, WT_, off_, gain_) { constexpr int nnb_ = DFF / 32, nit_ = (DM / 64) * nnb_; \
;     if (r < nit_) { const int kb_ = r / nnb_, nb_ = r % nnb_, c0_ = 32 * nb_; \
;         return TrDesc{(W_) + (size_t)(64 * kb_) * DFF + c0_, (WT_) + (size_t)(256 * (c0_ / 128) + (c0_ % 128) + (off_)) * DM + 64 * kb_, (gain_) + 64 * kb_, DFF, DM}; } r -= nit_; }
; __device__ __forceinline__ TrDesc p0_item(const Params& p, int it) {
;     unsigned char* ws = p.ws;
;     bf16_t* WAB_IN = (bf16_t*)(ws + WS_WAB_IN); bf16_t* WAB_OUT = (bf16_t*)(ws + WS_WAB_OUT); bf16_t* WGU0 = (bf16_t*)(ws + WS_WGU0); bf16_t* WDN0 = (bf16_t*)(ws + WS_WDN0);
;     bf16_t* WCD_IN = (bf16_t*)(ws + WS_WCD_IN); bf16_t* WGU1 = (bf16_t*)(ws + WS_WGU1);
;     bf16_t* WRG = (bf16_t*)(ws + WS_WRG);
;     int r = it;
;     TR_JOB(p.ab_w_in, AB_IN, DM, 0, 6144, WAB_IN, 0, p.norm_mix)
;     TR_JOB(p.ab_w_in, AB_IN, DM, 6160, 6144, WAB_IN, 6144, p.norm_mix)
;     TR_JOB(p.ab_w_out, DM, DM, 0, DM, WAB_OUT, 0, (const float*)nullptr)
;     TR_JOB_GU(p.ffn_w_gate, WGU0, 0, p.norm_ffn)
;     TR_JOB_GU(p.ffn_w_up, WGU0, 128, p.norm_ffn)
;     TR_JOB(p.ffn_w_down, DM, DFF, 0, DM, WDN0, 0, (const float*)nullptr)
;     TR_JOB(p.cd_w_in, CD_IN, DM, 0, CD_IN, WCD_IN, 0, p.norm_mix + DM)
;     TR_JOB_GU(p.ffn_w_gate + (size_t)DM * DFF, WGU1, 0, p.norm_ffn + DM)
;     TR_JOB_GU(p.ffn_w_up + (size_t)DM * DFF, WGU1, 128, p.norm_ffn + DM)
;     TR_JOB(p.cd_w_out, DM, DM, 0, DM, (bf16_t*)(ws + WS_WCD_OUT), 0, (const float*)nullptr)
;     const int mat = r / 32, rr = r % 32, kb_ = rr / 8, nb_ = rr % 8;
;     const float* W = (mat < 8 ? p.rg_w_x : p.rg_w_a) + (size_t)(mat & 7) * 65536;
;     return TrDesc{W + (size_t)(64 * kb_) * 256 + 32 * nb_, WRG + (size_t)mat * 65536 + (size_t)(32 * nb_) * 256 + 64 * kb_, nullptr, 256, 256};
; }
.Lcv_back_2:
.Lcv_job_dn0:
	s_load_dwordx2 s[60:61], s[24:25], 0x28
	s_load_dwordx2 s[62:63], s[24:25], 0xb8
	s_mov_b32 s6, 0x4000
	s_mov_b32 s7, 0x5600
	s_mov_b32 s75, 3
	s_and_b32 s10, s18, 31
	s_lshr_b32 s9, s18, 5
	s_add_i32 s9, s9, 12
	s_and_b32 s9, s9, 15
	s_sub_i32 s74, 171, s9
	s_lshr_b32 s74, s74, 4
	s_add_i32 s74, s74, 1
	s_lshl_b32 s11, s9, 6
	s_mul_i32 s11, s11, s6
	s_lshl_b32 s21, s10, 9
	s_add_u32 s11, s11, s21
	s_lshl_b32 s23, s10, 7
	s_mul_i32 s23, s23, s7
	s_lshl_b32 s26, s9, 7
	s_add_u32 s23, s23, s26
	s_mov_b32 s70, 0x1000000
	s_mov_b32 s71, 0
	s_mov_b32 s72, 0x800
	s_mov_b32 s73, 0
	s_waitcnt lgkmcnt(0)
	s_add_u32 s60, s60, s11
	s_addc_u32 s61, s61, 0
	s_add_u32 s62, s62, 0x12d00000
	s_addc_u32 s63, s63, 0
	s_add_u32 s62, s62, s23
	s_addc_u32 s63, s63, 0
	s_lshl_b32 s26, s7, 5
	s_add_u32 s64, s62, s26
	s_addc_u32 s65, s63, 0
	s_add_u32 s66, s64, s26
	s_addc_u32 s67, s65, 0
	s_add_u32 s68, s66, s26
	s_addc_u32 s69, s67, 0
	s_mov_b32 s8, 0
	s_branch .Lcv_run
.Lcv_back_3:
.Lcv_job_cdi:
	s_load_dwordx2 s[60:61], s[24:25], 0x60
	s_load_dwordx2 s[62:63], s[24:25], 0xb8
	s_load_dwordx2 s[4:5], s[24:25], 0x8
	s_mov_b32 s6, 0xa000
	s_mov_b32 s7, 0x2000
	s_mov_b32 s75, 4
	s_and_b32 s9, s18, 63
	s_lshr_b32 s10, s18, 6
	s_add_i32 s10, s10, 6
	s_and_b32 s10, s10, 7
	s_sub_i32 s74, 79, s10
	s_lshr_b32 s74, s74, 3
	s_add_i32 s74, s74, 1
	s_lshl_b32 s11, s9, 6
	s_mul_i32 s11, s11, s6
	s_lshl_b32 s21, s10, 9
	s_add_u32 s11, s11, s21
	s_mul_i32 s23, s10, 128
	s_mul_i32 s23, s23, s7
	s_lshl_b32 s26, s9, 7
	s_add_u32 s23, s23, s26
	s_mov_b32 s70, 0x1000
	s_mov_b32 s71, 0
	s_mov_b32 s72, 0x800000
	s_mov_b32 s73, 0
	s_waitcnt lgkmcnt(0)
	s_add_u32 s60, s60, s11
	s_addc_u32 s61, s61, 0
	s_add_u32 s62, s62, 0x18300000
	s_addc_u32 s63, s63, 0
	s_add_u32 s62, s62, s23
	s_addc_u32 s63, s63, 0
	s_lshl_b32 s26, s7, 5
	s_add_u32 s64, s62, s26
	s_addc_u32 s65, s63, 0
	s_add_u32 s66, s64, s26
	s_addc_u32 s67, s65, 0
	s_add_u32 s68, s66, s26
	s_addc_u32 s69, s67, 0
	s_add_u32 s4, s4, 0x4000
	s_addc_u32 s5, s5, 0
	s_lshl_b32 s26, s9, 8
	s_add_u32 s4, s4, s26
	s_addc_u32 s5, s5, 0
	s_mov_b32 s8, 1
	s_branch .Lcv_run
.Lcv_back_4:
.Lcv_job_rgx:
	s_load_dwordx2 s[60:61], s[24:25], 0x78
	s_load_dwordx2 s[62:63], s[24:25], 0xb8
	s_mov_b32 s6, 0x400
	s_mov_b32 s7, 0x200
	s_mov_b32 s75, 5
	s_sub_i32 s9, s18, 384
	s_cmp_lt_u32 s9, 64
	s_cselect_b32 s74, 1, 0
	s_and_b32 s9, s9, 63
	s_lshr_b32 s10, s9, 3
	s_bfe_u32 s21, s9, 0x20001
	s_and_b32 s26, s9, 1
	s_lshl_b32 s11, s10, 18
	s_lshl_b32 s27, s21, 16
	s_add_u32 s11, s11, s27
	s_lshl_b32 s27, s26, 9
	s_add_u32 s11, s11, s27
	s_lshl_b32 s23, s10, 17
	s_lshl_b32 s27, s26, 16
	s_add_u32 s23, s23, s27
	s_lshl_b32 s27, s21, 7
	s_add_u32 s23, s23, s27
	s_mov_b32 s70, 0
	s_mov_b32 s71, 0
	s_mov_b32 s72, 0
	s_mov_b32 s73, 0
	s_waitcnt lgkmcnt(0)
	s_add_u32 s60, s60, s11
	s_addc_u32 s61, s61, 0
	s_add_u32 s62, s62, 0x2f600000
	s_addc_u32 s63, s63, 0
	s_add_u32 s62, s62, s23
	s_addc_u32 s63, s63, 0
	s_lshl_b32 s26, s7, 5
	s_add_u32 s64, s62, s26
	s_addc_u32 s65, s63, 0
	s_add_u32 s66, s64, s26
	s_addc_u32 s67, s65, 0
	s_add_u32 s68, s66, s26
	s_addc_u32 s69, s67, 0
	s_mov_b32 s8, 0
	s_branch .Lcv_run
.Lcv_back_5:
.Lcv_job_rga:
	s_load_dwordx2 s[60:61], s[24:25], 0x88
	s_load_dwordx2 s[62:63], s[24:25], 0xb8
	s_mov_b32 s6, 0x400
	s_mov_b32 s7, 0x200
	s_mov_b32 s75, 6
	s_sub_i32 s9, s18, 448
	s_cmp_lt_u32 s9, 64
	s_cselect_b32 s74, 1, 0
	s_and_b32 s9, s9, 63
	s_lshr_b32 s10, s9, 3
	s_bfe_u32 s21, s9, 0x20001
	s_and_b32 s26, s9, 1
	s_lshl_b32 s11, s10, 18
	s_lshl_b32 s27, s21, 16
	s_add_u32 s11, s11, s27
	s_lshl_b32 s27, s26, 9
	s_add_u32 s11, s11, s27
	s_lshl_b32 s23, s10, 17
	s_lshl_b32 s27, s26, 16
	s_add_u32 s23, s23, s27
	s_lshl_b32 s27, s21, 7
	s_add_u32 s23, s23, s27
	s_mov_b32 s70, 0
	s_mov_b32 s71, 0
	s_mov_b32 s72, 0
	s_mov_b32 s73, 0
	s_waitcnt lgkmcnt(0)
	s_add_u32 s60, s60, s11
	s_addc_u32 s61, s61, 0
	s_add_u32 s62, s62, 0x2f700000
	s_addc_u32 s63, s63, 0
	s_add_u32 s62, s62, s23
	s_addc_u32 s63, s63, 0
	s_lshl_b32 s26, s7, 5
	s_add_u32 s64, s62, s26
	s_addc_u32 s65, s63, 0
	s_add_u32 s66, s64, s26
	s_addc_u32 s67, s65, 0
	s_add_u32 s68, s66, s26
	s_addc_u32 s69, s67, 0
	s_mov_b32 s8, 0
	s_branch .Lcv_run

; #define LAS __attribute__((address_space(3)))
; __device__ __forceinline__ void p0b_convert(const Params& p, LAS unsigned char* lds, int tw, int ntw, int wave, int lane) {
;     P0Item pi{&p, P0A_ITEMS}; tr_run(pi, tw, ntw, P0_NITEMS - P0A_ITEMS, (LAS float*)(lds + wave * 8704), lane);
; }
.Lcv_ret:
	s_cmp_eq_u32 s75, 0
	s_cbranch_scc1 .Lcv_back_0
	s_cmp_eq_u32 s75, 1
	s_cbranch_scc1 .Lcv_back_1
	s_cmp_eq_u32 s75, 2
	s_cbranch_scc1 .Lcv_back_2
	s_cmp_eq_u32 s75, 3
	s_cbranch_scc1 .Lcv_back_3
	s_cmp_eq_u32 s75, 4
	s_cbranch_scc1 .Lcv_back_4
	s_cmp_eq_u32 s75, 5
	s_cbranch_scc1 .Lcv_back_5
	s_cmp_eq_u32 s75, 6
	s_cbranch_scc1 .Lcv_back_6
.Lcv_done:
	s_branch .LBB0_663

; template <int layer>
; __device__ __forceinline__ void layer_phases(const Params& p, LAS unsigned char* lds, const XcdBarrier& bar, int lo, int hi, int G, int gw, int ngw, int wave, int lane) {
;     ...
;                 if (G == 256) {
;                     if ((int)blockIdx.x < NG) { pg8::StaticOrder S; S.init(MTOK, AB_MAIN, NG, (int)blockIdx.x); pg8::gemm_phase<pg8::EpiBf16<true>, pg8::StaticOrder, true, true>(lds, g, S, E); }
;                     else p0b_convert(p, lds, ((int)blockIdx.x - NG) * NWAVES + wave, (G - NG) * NWAVES, wave, lane);
.Lgs_back_0:
.Lgs_job_g1:
	s_load_dwordx2 s[60:61], s[24:25], 0x18
	s_load_dwordx2 s[62:63], s[24:25], 0xb8
	s_load_dwordx2 s[4:5], s[24:25], 0x10
	s_mov_b32 s6, 0xac00
	s_mov_b32 s7, 0x2000
	s_mov_b32 s75, 1
	s_and_b32 s9, s18, 63
	s_lshr_b32 s10, s18, 6
	s_add_i32 s10, s10, 2
	s_cmp_ge_u32 s10, 24
	s_cselect_b32 s74, 24, 0
	s_sub_i32 s10, s10, s74
	s_sub_i32 s74, 85, s10
	s_mul_i32 s74, s74, 2731
	s_lshr_b32 s74, s74, 16
	s_add_i32 s74, s74, 1
	s_lshl_b32 s11, s9, 6
	s_mul_i32 s11, s11, s6
	s_lshl_b32 s21, s10, 9
	s_add_u32 s11, s11, s21
	s_mul_i32 s23, s10, 256
	s_mul_i32 s23, s23, s7
	s_lshl_b32 s26, s9, 7
	s_add_u32 s23, s23, s26
	s_mov_b32 s70, 0x3000
	s_mov_b32 s71, 0
	s_mov_b32 s72, 0x3000000
	s_mov_b32 s73, 0
	s_waitcnt lgkmcnt(0)
	s_add_u32 s60, s60, 0xac00000
	s_addc_u32 s61, s61, 0
	s_add_u32 s60, s60, s11
	s_addc_u32 s61, s61, 0
	s_add_u32 s62, s62, 0x1f300000
	s_addc_u32 s63, s63, 0
	s_add_u32 s62, s62, s23
	s_addc_u32 s63, s63, 0
	s_lshl_b32 s26, s7, 5
	s_add_u32 s64, s62, s26
	s_addc_u32 s65, s63, 0
	s_add_u32 s66, s64, s26
	s_addc_u32 s67, s65, 0
	s_add_u32 s68, s66, s26
	s_addc_u32 s69, s67, 0
	s_add_u32 s4, s4, 0x4000
	s_addc_u32 s5, s5, 0
	s_lshl_b32 s26, s9, 8
	s_add_u32 s4, s4, s26
	s_addc_u32 s5, s5, 0
	s_mov_b32 s8, 1
	s_branch .Lgs_run
.Lgs_back_1:
.Lgs_job_cdo:
	s_load_dwordx2 s[60:61], s[24:25], 0xa0
	s_load_dwordx2 s[62:63], s[24:25], 0xb8
	s_mov_b32 s6, 0x4000
	s_mov_b32 s7, 0x2000
	s_mov_b32 s75, 2
	s_and_b32 s9, s18, 63
	s_lshr_b32 s10, s18, 6
	s_add_i32 s10, s10, 10
	s_cmp_ge_u32 s10, 24
	s_cselect_b32 s74, 24, 0
	s_sub_i32 s10, s10, s74
	s_sub_i32 s74, 31, s10
	s_mul_i32 s74, s74, 2731
	s_lshr_b32 s74, s74, 16
	s_add_i32 s74, s74, 1
	s_lshl_b32 s11, s9, 6
	s_mul_i32 s11, s11, s6
	s_lshl_b32 s21, s10, 9
	s_add_u32 s11, s11, s21
	s_mul_i32 s23, s10, 128
	s_mul_i32 s23, s23, s7
	s_lshl_b32 s26, s9, 7
	s_add_u32 s23, s23, s26
	s_mov_b32 s70, 0x3000
	s_mov_b32 s71, 0
	s_mov_b32 s72, 0x1800000
	s_mov_b32 s73, 0
	s_waitcnt lgkmcnt(0)
	s_add_u32 s60, s60, s11
	s_addc_u32 s61, s61, 0
	s_add_u32 s62, s62, 0x1d300000
	s_addc_u32 s63, s63, 0
	s_add_u32 s62, s62, s23
	s_addc_u32 s63, s63, 0
	s_lshl_b32 s26, s7, 5
	s_add_u32 s64, s62, s26
	s_addc_u32 s65, s63, 0
	s_add_u32 s66, s64, s26
	s_addc_u32 s67, s65, 0
	s_add_u32 s68, s66, s26
	s_addc_u32 s69, s67, 0
	s_mov_b32 s8, 0
	s_branch .Lgs_run

; __device__ __forceinline__ void xcd_barrier_complete(unsigned* bar, unsigned x, unsigned& nloc, unsigned& nx) {
;     const unsigned G = gridDim.x * gridDim.y * gridDim.z;
;     unsigned sum, cnt, mine, sp = 0u;
;     for (;;) {
;         sum = 0u; cnt = 0u; mine = 0u;
; #pragma unroll
;         for (unsigned j = 0; j < 16; ++j) { const unsigned c = xb_ld(&bar[XB_XCNT(j)]); sum += c; cnt += (c > 0u) ? 1u : 0u; mine = (j == x) ? c : mine; }
;         if (sum == G) break;
;         __builtin_amdgcn_s_sleep(1);
;         if ((++sp & 255u) == 0u) { if (xb_ld(&bar[XB_TMO])) break; if (sp > XB_SPIN_CAP) { atomicAdd(&bar[XB_TMO], 1u); break; } }
;     }
;     nloc = mine > 0u ? mine : 1u; nx = cnt > 0u ? cnt : 1u;
; }
; __device__ __forceinline__ void xcd_barrier(const XcdBarrier& b) {
;     asm volatile("s_waitcnt vmcnt(0)" ::: "memory");
;     __syncthreads();
;     if (threadIdx.x == 0) {
;         unsigned* bar = b.bar;
;         __builtin_amdgcn_s_waitcnt(0);
;         unsigned nloc = b.st[0], nx = b.st[1];
;         if (nloc == 0u) { xcd_barrier_complete(bar, b.x, nloc, nx); b.st[0] = nloc; b.st[1] = nx; }
; template <int layer>
; __device__ __forceinline__ void layer_phases(const Params& p, LAS unsigned char* lds, const XcdBarrier& bar, int lo, int hi, int G, int gw, int ngw, int wave, int lane) {
;     ...
;                 if (G == 256) {
;                     if ((int)blockIdx.x < NG) { pg8::StaticOrder S; S.init(MTOK, AB_MAIN, NG, (int)blockIdx.x); pg8::gemm_phase<pg8::EpiBf16<true>, pg8::StaticOrder, true, true>(lds, g, S, E); }
;                     else p0b_convert(p, lds, ((int)blockIdx.x - NG) * NWAVES + wave, (G - NG) * NWAVES, wave, lane);
;                 } else {
;                     p0b_convert(p, lds, gw, ngw, wave, lane); __syncthreads();
;                     pg8::StaticOrder S; S.init(MTOK, AB_MAIN, G, (int)blockIdx.x); pg8::gemm_phase<pg8::EpiBf16<true>, pg8::StaticOrder, true, true>(lds, g, S, E);
;                 }
;             } else {
;                 pg8::Gemm g{U, (const bf16_t*)(ws + WS_WCD_IN), MTOK, CD_IN, DM}; pg8::StaticOrder S; S.init(MTOK, CD_IN, G, (int)blockIdx.x);
;                 pg8::EpiBf16<true> E{PROJ, CD_IN, SSQ + 1 * MTOK};
;                 for (int rep = 0; rep < REP_GEMM; ++rep) { pg8::gemm_phase<pg8::EpiBf16<true>, pg8::StaticOrder, true, true>(lds, g, S, E); __syncthreads(); }
;             }
.Lgs_ret:
	s_cmp_eq_u32 s75, 0
	s_cbranch_scc1 .Lgs_back_0
	s_cmp_eq_u32 s75, 1
	s_cbranch_scc1 .Lgs_back_1
	s_cmp_eq_u32 s75, 2
	s_cbranch_scc1 .Lgs_back_2
.Lgs_done:
	v_readlane_b32 s40, v240, 31
	v_readlane_b32 s41, v240, 32
	s_cmp_lt_i32 s41, 3
	v_readlane_b32 s42, v240, 33
	v_readlane_b32 s43, v240, 34
	s_cbranch_scc1 .LBB0_734
	s_waitcnt vmcnt(0)
	s_barrier
	s_mov_b64 s[0:1], exec
	v_readlane_b32 s2, v240, 23
	v_readlane_b32 s3, v240, 24
	s_and_b64 s[2:3], s[0:1], s[2:3]
	s_mov_b64 exec, s[2:3]
	s_cbranch_execz .LBB0_733
	s_add_i32 s2, 0, 0x20160
	s_waitcnt vmcnt(7)
	v_mov_b32_e32 v2, s2
	s_waitcnt vmcnt(0) expcnt(0) lgkmcnt(0)
	ds_read_b32 v4, v2
	s_add_i32 s2, 0, 0x20164
	v_mov_b32_e32 v2, s2
	ds_read_b32 v2, v2
	s_waitcnt lgkmcnt(1)
	v_cmp_ne_u32_e32 vcc, 0, v4
	s_cbranch_vccnz .LBB0_697
	v_readlane_b32 s2, v240, 2
	v_readlane_b32 s3, v240, 3
	s_load_dwordx2 s[6:7], s[2:3], 0x4
	v_readlane_b32 s8, v240, 20
	v_readlane_b32 s9, v240, 21
	s_add_u32 s2, s8, 0x1000
	s_addc_u32 s3, s9, 0
	s_add_u32 s4, s8, 0x1100
	s_addc_u32 s5, s9, 0
	s_waitcnt lgkmcnt(0)
	s_mul_i32 s16, s6, s92
	s_add_u32 s6, s8, 0x1200
	s_mul_i32 s16, s16, s7
	s_addc_u32 s7, s9, 0
	s_add_u32 s8, s8, 0x1300
	s_addc_u32 s9, s9, 0
	s_mov_b32 s17, 1
	v_mov_b32_e32 v18, 0
	s_branch .LBB0_685
